# plus: Q GEMM epilogue rope-table loads issued one row-group ahead
# speedup vs baseline: 1.0072x; 1.0039x over previous
.LBB0_433:
	s_add_u32 s6, s78, 0x100
	s_addc_u32 s7, s79, 0
	s_add_i32 s2, 0, 0x10000
	v_add_u32_e32 v0, s2, v153
	ds_read_b128 v[142:145], v0
	ds_read_b128 v[146:149], v0 offset:1024
	ds_read_b128 v[156:159], v0 offset:2048
	ds_read_b128 v[160:163], v0 offset:3072
	s_cmp_eq_u32 s44, 4
	s_cselect_b32 s83, s75, s7
	s_cselect_b32 s82, s74, s6
	s_cselect_b32 s81, s11, s46
	s_cselect_b32 s80, s24, s25
	v_lshl_add_u64 v[150:151], s[78:79], 0, v[138:139]
	s_add_i32 m0, s58, 0xc000
	ds_read_b128 v[188:191], v155
	ds_read_b128 v[192:195], v155 offset:1024
	ds_read_b128 v[196:199], v155 offset:2048
	ds_read_b128 v[200:203], v155 offset:3072
	ds_read_b128 v[216:219], v155 offset:4096
	ds_read_b128 v[220:223], v155 offset:5120
	ds_read_b128 v[224:227], v155 offset:6144
	ds_read_b128 v[228:231], v155 offset:7168
	global_load_lds_dwordx4 v[150:151], off
	v_lshl_add_u64 v[150:151], s[78:79], 0, v[140:141]
	s_add_i32 m0, s58, 0xe000
	s_nop 0
	global_load_lds_dwordx4 v[150:151], off
	s_waitcnt lgkmcnt(8)
	s_barrier
	s_waitcnt lgkmcnt(7)
	v_mfma_f32_16x16x32_bf16 v[126:129], v[142:145], v[188:191], v[126:129]
	v_mfma_f32_16x16x32_bf16 v[122:125], v[156:159], v[188:191], v[122:125]
	s_waitcnt lgkmcnt(5)
	v_mfma_f32_16x16x32_bf16 v[110:113], v[142:145], v[196:199], v[110:113]
	v_mfma_f32_16x16x32_bf16 v[106:109], v[156:159], v[196:199], v[106:109]
	s_waitcnt lgkmcnt(3)
	v_mfma_f32_16x16x32_bf16 v[94:97], v[142:145], v[216:219], v[94:97]
	v_mfma_f32_16x16x32_bf16 v[90:93], v[156:159], v[216:219], v[90:93]
	s_waitcnt lgkmcnt(1)
	v_mfma_f32_16x16x32_bf16 v[78:81], v[142:145], v[224:227], v[78:81]
	v_mfma_f32_16x16x32_bf16 v[74:77], v[156:159], v[224:227], v[74:77]
	v_mfma_f32_16x16x32_bf16 v[126:129], v[146:149], v[192:195], v[126:129]
	v_mfma_f32_16x16x32_bf16 v[122:125], v[160:163], v[192:195], v[122:125]
	v_mfma_f32_16x16x32_bf16 v[110:113], v[146:149], v[200:203], v[110:113]
	v_mfma_f32_16x16x32_bf16 v[106:109], v[160:163], v[200:203], v[106:109]
	v_mfma_f32_16x16x32_bf16 v[94:97], v[146:149], v[220:223], v[94:97]
	v_mfma_f32_16x16x32_bf16 v[90:93], v[160:163], v[220:223], v[90:93]
	s_waitcnt lgkmcnt(0)
	v_mfma_f32_16x16x32_bf16 v[78:81], v[146:149], v[228:231], v[78:81]
	v_mfma_f32_16x16x32_bf16 v[74:77], v[160:163], v[228:231], v[74:77]
	s_barrier
	s_add_i32 s17, 0, 0x14000
	s_add_i32 s2, s2, s3
	v_add_u32_e32 v0, s17, v153
	v_lshl_add_u64 v[150:151], s[80:81], 0, v[134:135]
	s_mov_b32 m0, s2
	ds_read_b128 v[232:235], v0
	ds_read_b128 v[236:239], v0 offset:1024
	ds_read_b128 v[240:243], v0 offset:2048
	ds_read_b128 v[244:247], v0 offset:3072
	global_load_lds_dwordx4 v[150:151], off
	v_lshl_add_u64 v[164:165], s[80:81], 0, v[130:131]
	s_add_i32 m0, s2, 0x2000
	s_nop 0
	global_load_lds_dwordx4 v[164:165], off
	s_barrier
	s_waitcnt lgkmcnt(3)
	v_mfma_f32_16x16x32_bf16 v[118:121], v[232:235], v[188:191], v[118:121]
	s_waitcnt lgkmcnt(1)
	v_mfma_f32_16x16x32_bf16 v[114:117], v[240:243], v[188:191], v[114:117]
	v_mfma_f32_16x16x32_bf16 v[102:105], v[232:235], v[196:199], v[102:105]
	v_mfma_f32_16x16x32_bf16 v[98:101], v[240:243], v[196:199], v[98:101]
	v_mfma_f32_16x16x32_bf16 v[86:89], v[232:235], v[216:219], v[86:89]
	v_mfma_f32_16x16x32_bf16 v[82:85], v[240:243], v[216:219], v[82:85]
	v_mfma_f32_16x16x32_bf16 v[70:73], v[232:235], v[224:227], v[70:73]
	v_mfma_f32_16x16x32_bf16 v[66:69], v[240:243], v[224:227], v[66:69]
	v_mfma_f32_16x16x32_bf16 v[118:121], v[236:239], v[192:195], v[118:121]
	s_waitcnt lgkmcnt(0)
	v_mfma_f32_16x16x32_bf16 v[114:117], v[244:247], v[192:195], v[114:117]
	v_mfma_f32_16x16x32_bf16 v[102:105], v[236:239], v[200:203], v[102:105]
	v_mfma_f32_16x16x32_bf16 v[98:101], v[244:247], v[200:203], v[98:101]
	v_mfma_f32_16x16x32_bf16 v[86:89], v[236:239], v[220:223], v[86:89]
	v_mfma_f32_16x16x32_bf16 v[82:85], v[244:247], v[220:223], v[82:85]
	v_mfma_f32_16x16x32_bf16 v[70:73], v[236:239], v[228:231], v[70:73]
	v_mfma_f32_16x16x32_bf16 v[66:69], v[244:247], v[228:231], v[66:69]
	s_mov_b32 m0, s58
	v_lshl_add_u64 v[204:205], s[82:83], 0, v[136:137]
	s_barrier
	ds_read_b128 v[188:191], v155 offset:16384
	ds_read_b128 v[192:195], v155 offset:17408
	ds_read_b128 v[196:199], v155 offset:18432
	ds_read_b128 v[200:203], v155 offset:19456
	ds_read_b128 v[216:219], v155 offset:20480
	ds_read_b128 v[220:223], v155 offset:21504
	ds_read_b128 v[224:227], v155 offset:22528
	ds_read_b128 v[228:231], v155 offset:23552
	global_load_lds_dwordx4 v[204:205], off
	v_lshl_add_u64 v[248:249], s[82:83], 0, v[132:133]
	s_mov_b32 m0, s69
	s_nop 0
	global_load_lds_dwordx4 v[248:249], off
	s_barrier
	s_waitcnt lgkmcnt(7)
	v_mfma_f32_16x16x32_bf16 v[62:65], v[142:145], v[188:191], v[62:65]
	v_mfma_f32_16x16x32_bf16 v[58:61], v[156:159], v[188:191], v[58:61]
	s_waitcnt lgkmcnt(5)
	v_mfma_f32_16x16x32_bf16 v[46:49], v[142:145], v[196:199], v[46:49]
	v_mfma_f32_16x16x32_bf16 v[42:45], v[156:159], v[196:199], v[42:45]
	s_waitcnt lgkmcnt(3)
	v_mfma_f32_16x16x32_bf16 v[30:33], v[142:145], v[216:219], v[30:33]
	v_mfma_f32_16x16x32_bf16 v[26:29], v[156:159], v[216:219], v[26:29]
	s_waitcnt lgkmcnt(1)
	v_mfma_f32_16x16x32_bf16 v[14:17], v[142:145], v[224:227], v[14:17]
	v_mfma_f32_16x16x32_bf16 v[10:13], v[156:159], v[224:227], v[10:13]
	v_mfma_f32_16x16x32_bf16 v[62:65], v[146:149], v[192:195], v[62:65]
	v_mfma_f32_16x16x32_bf16 v[58:61], v[160:163], v[192:195], v[58:61]
	v_mfma_f32_16x16x32_bf16 v[46:49], v[146:149], v[200:203], v[46:49]
	v_mfma_f32_16x16x32_bf16 v[42:45], v[160:163], v[200:203], v[42:45]
	v_mfma_f32_16x16x32_bf16 v[30:33], v[146:149], v[220:223], v[30:33]
	v_mfma_f32_16x16x32_bf16 v[26:29], v[160:163], v[220:223], v[26:29]
	s_waitcnt lgkmcnt(0)
	v_mfma_f32_16x16x32_bf16 v[14:17], v[146:149], v[228:231], v[14:17]
	v_mfma_f32_16x16x32_bf16 v[10:13], v[160:163], v[228:231], v[10:13]
	s_barrier
	s_add_u32 s26, s80, 0x20000
	s_addc_u32 s27, s81, 0
	s_add_i32 s2, s17, s3
	v_lshl_add_u64 v[142:143], s[26:27], 0, v[134:135]
	s_mov_b32 m0, s2
	s_nop 0
	global_load_lds_dwordx4 v[142:143], off
	v_lshl_add_u64 v[142:143], s[26:27], 0, v[130:131]
	s_add_i32 m0, s2, 0x2000
	s_nop 0
	global_load_lds_dwordx4 v[142:143], off
	s_waitcnt vmcnt(6)
	s_barrier
	v_mfma_f32_16x16x32_bf16 v[54:57], v[232:235], v[188:191], v[54:57]
	v_mfma_f32_16x16x32_bf16 v[50:53], v[240:243], v[188:191], v[50:53]
	v_mfma_f32_16x16x32_bf16 v[38:41], v[232:235], v[196:199], v[38:41]
	v_mfma_f32_16x16x32_bf16 v[34:37], v[240:243], v[196:199], v[34:37]
	v_mfma_f32_16x16x32_bf16 v[22:25], v[232:235], v[216:219], v[22:25]
	v_mfma_f32_16x16x32_bf16 v[18:21], v[240:243], v[216:219], v[18:21]
	v_mfma_f32_16x16x32_bf16 v[6:9], v[232:235], v[224:227], v[6:9]
	v_mfma_f32_16x16x32_bf16 v[2:5], v[240:243], v[224:227], v[2:5]
	v_mfma_f32_16x16x32_bf16 v[54:57], v[236:239], v[192:195], v[54:57]
	v_mfma_f32_16x16x32_bf16 v[50:53], v[244:247], v[192:195], v[50:53]
	v_mfma_f32_16x16x32_bf16 v[38:41], v[236:239], v[200:203], v[38:41]
	v_mfma_f32_16x16x32_bf16 v[34:37], v[244:247], v[200:203], v[34:37]
	v_mfma_f32_16x16x32_bf16 v[22:25], v[236:239], v[220:223], v[22:25]
	v_mfma_f32_16x16x32_bf16 v[18:21], v[244:247], v[220:223], v[18:21]
	v_mfma_f32_16x16x32_bf16 v[6:9], v[236:239], v[228:231], v[6:9]
	v_mfma_f32_16x16x32_bf16 v[2:5], v[244:247], v[228:231], v[2:5]
	s_add_i32 s2, 0, 0x18000
	v_add_u32_e32 v0, s2, v153
	s_barrier
	ds_read_b128 v[142:145], v0
	ds_read_b128 v[146:149], v0 offset:1024
	ds_read_b128 v[156:159], v0 offset:2048
	ds_read_b128 v[160:163], v0 offset:3072
	s_add_u32 s26, s82, 0xd0000
	s_addc_u32 s27, s83, 0
	s_mov_b32 m0, s92
	v_lshl_add_u64 v[232:233], s[26:27], 0, v[136:137]
	ds_read_b128 v[188:191], v155 offset:32768
	ds_read_b128 v[192:195], v155 offset:33792
	ds_read_b128 v[196:199], v155 offset:34816
	ds_read_b128 v[200:203], v155 offset:35840
	ds_read_b128 v[216:219], v155 offset:36864
	ds_read_b128 v[220:223], v155 offset:37888
	ds_read_b128 v[224:227], v155 offset:38912
	ds_read_b128 v[228:231], v155 offset:39936
	global_load_lds_dwordx4 v[232:233], off
	v_lshl_add_u64 v[232:233], s[26:27], 0, v[132:133]
	s_mov_b32 m0, s93
	s_nop 0
	global_load_lds_dwordx4 v[232:233], off
	s_waitcnt lgkmcnt(8)
	s_barrier
	s_waitcnt lgkmcnt(7)
	v_mfma_f32_16x16x32_bf16 v[126:129], v[142:145], v[188:191], v[126:129]
	v_mfma_f32_16x16x32_bf16 v[122:125], v[156:159], v[188:191], v[122:125]
	s_waitcnt lgkmcnt(5)
	v_mfma_f32_16x16x32_bf16 v[110:113], v[142:145], v[196:199], v[110:113]
	v_mfma_f32_16x16x32_bf16 v[106:109], v[156:159], v[196:199], v[106:109]
	s_waitcnt lgkmcnt(3)
	v_mfma_f32_16x16x32_bf16 v[94:97], v[142:145], v[216:219], v[94:97]
	v_mfma_f32_16x16x32_bf16 v[90:93], v[156:159], v[216:219], v[90:93]
	s_waitcnt lgkmcnt(1)
	v_mfma_f32_16x16x32_bf16 v[78:81], v[142:145], v[224:227], v[78:81]
	v_mfma_f32_16x16x32_bf16 v[74:77], v[156:159], v[224:227], v[74:77]
	v_mfma_f32_16x16x32_bf16 v[126:129], v[146:149], v[192:195], v[126:129]
	v_mfma_f32_16x16x32_bf16 v[122:125], v[160:163], v[192:195], v[122:125]
	v_mfma_f32_16x16x32_bf16 v[110:113], v[146:149], v[200:203], v[110:113]
	v_mfma_f32_16x16x32_bf16 v[106:109], v[160:163], v[200:203], v[106:109]
	v_mfma_f32_16x16x32_bf16 v[94:97], v[146:149], v[220:223], v[94:97]
	v_mfma_f32_16x16x32_bf16 v[90:93], v[160:163], v[220:223], v[90:93]
	s_waitcnt lgkmcnt(0)
	v_mfma_f32_16x16x32_bf16 v[78:81], v[146:149], v[228:231], v[78:81]
	v_mfma_f32_16x16x32_bf16 v[74:77], v[160:163], v[228:231], v[74:77]
	s_barrier
	s_add_i32 s17, 0, 0x1c000
	s_add_i32 s2, s2, s3
	v_add_u32_e32 v0, s17, v153
	v_lshl_add_u64 v[150:151], v[150:151], 0, s[28:29]
	s_mov_b32 m0, s2
	ds_read_b128 v[232:235], v0
	ds_read_b128 v[236:239], v0 offset:1024
	ds_read_b128 v[240:243], v0 offset:2048
	ds_read_b128 v[244:247], v0 offset:3072
	global_load_lds_dwordx4 v[150:151], off
	v_lshl_add_u64 v[150:151], v[164:165], 0, s[28:29]
	s_add_i32 m0, s2, 0x2000
	s_nop 0
	global_load_lds_dwordx4 v[150:151], off
	s_barrier
	s_waitcnt lgkmcnt(3)
	v_mfma_f32_16x16x32_bf16 v[118:121], v[232:235], v[188:191], v[118:121]
	s_waitcnt lgkmcnt(1)
	v_mfma_f32_16x16x32_bf16 v[114:117], v[240:243], v[188:191], v[114:117]
	v_mfma_f32_16x16x32_bf16 v[102:105], v[232:235], v[196:199], v[102:105]
	v_mfma_f32_16x16x32_bf16 v[98:101], v[240:243], v[196:199], v[98:101]
	v_mfma_f32_16x16x32_bf16 v[86:89], v[232:235], v[216:219], v[86:89]
	v_mfma_f32_16x16x32_bf16 v[82:85], v[240:243], v[216:219], v[82:85]
	v_mfma_f32_16x16x32_bf16 v[70:73], v[232:235], v[224:227], v[70:73]
	v_mfma_f32_16x16x32_bf16 v[66:69], v[240:243], v[224:227], v[66:69]
	v_mfma_f32_16x16x32_bf16 v[118:121], v[236:239], v[192:195], v[118:121]
	s_waitcnt lgkmcnt(0)
	v_mfma_f32_16x16x32_bf16 v[114:117], v[244:247], v[192:195], v[114:117]
	v_mfma_f32_16x16x32_bf16 v[102:105], v[236:239], v[200:203], v[102:105]
	v_mfma_f32_16x16x32_bf16 v[98:101], v[244:247], v[200:203], v[98:101]
	v_mfma_f32_16x16x32_bf16 v[86:89], v[236:239], v[220:223], v[86:89]
	v_mfma_f32_16x16x32_bf16 v[82:85], v[244:247], v[220:223], v[82:85]
	v_mfma_f32_16x16x32_bf16 v[70:73], v[236:239], v[228:231], v[70:73]
	v_mfma_f32_16x16x32_bf16 v[66:69], v[244:247], v[228:231], v[66:69]
	s_mov_b32 m0, s72
	v_lshl_add_u64 v[150:151], v[204:205], 0, s[28:29]
	s_barrier
	ds_read_b128 v[188:191], v155 offset:49152
	ds_read_b128 v[192:195], v155 offset:50176
	ds_read_b128 v[196:199], v155 offset:51200
	ds_read_b128 v[200:203], v155 offset:52224
	ds_read_b128 v[216:219], v155 offset:53248
	ds_read_b128 v[220:223], v155 offset:54272
	ds_read_b128 v[224:227], v155 offset:55296
	ds_read_b128 v[228:231], v155 offset:56320
	global_load_lds_dwordx4 v[150:151], off
	v_lshl_add_u64 v[150:151], v[248:249], 0, s[28:29]
	s_mov_b32 m0, s73
	s_nop 0
	global_load_lds_dwordx4 v[150:151], off
	s_barrier
	s_waitcnt lgkmcnt(7)
	v_mfma_f32_16x16x32_bf16 v[62:65], v[142:145], v[188:191], v[62:65]
	v_mfma_f32_16x16x32_bf16 v[58:61], v[156:159], v[188:191], v[58:61]
	s_waitcnt lgkmcnt(5)
	v_mfma_f32_16x16x32_bf16 v[46:49], v[142:145], v[196:199], v[46:49]
	v_mfma_f32_16x16x32_bf16 v[42:45], v[156:159], v[196:199], v[42:45]
	s_waitcnt lgkmcnt(3)
	v_mfma_f32_16x16x32_bf16 v[30:33], v[142:145], v[216:219], v[30:33]
	v_mfma_f32_16x16x32_bf16 v[26:29], v[156:159], v[216:219], v[26:29]
	s_waitcnt lgkmcnt(1)
	v_mfma_f32_16x16x32_bf16 v[14:17], v[142:145], v[224:227], v[14:17]
	v_mfma_f32_16x16x32_bf16 v[10:13], v[156:159], v[224:227], v[10:13]
	v_mfma_f32_16x16x32_bf16 v[62:65], v[146:149], v[192:195], v[62:65]
	v_mfma_f32_16x16x32_bf16 v[58:61], v[160:163], v[192:195], v[58:61]
	v_mfma_f32_16x16x32_bf16 v[46:49], v[146:149], v[200:203], v[46:49]
	v_mfma_f32_16x16x32_bf16 v[42:45], v[160:163], v[200:203], v[42:45]
	v_mfma_f32_16x16x32_bf16 v[30:33], v[146:149], v[220:223], v[30:33]
	v_mfma_f32_16x16x32_bf16 v[26:29], v[160:163], v[220:223], v[26:29]
	s_waitcnt lgkmcnt(0)
	v_mfma_f32_16x16x32_bf16 v[14:17], v[146:149], v[228:231], v[14:17]
	v_mfma_f32_16x16x32_bf16 v[10:13], v[160:163], v[228:231], v[10:13]
	s_barrier
	s_add_u32 s26, s80, 0x20080
	s_addc_u32 s27, s81, 0
	s_add_i32 s2, s17, s3
	v_lshl_add_u64 v[142:143], s[26:27], 0, v[134:135]
	s_mov_b32 m0, s2
	s_nop 0
	global_load_lds_dwordx4 v[142:143], off
	v_lshl_add_u64 v[142:143], s[26:27], 0, v[130:131]
	s_add_i32 m0, s2, 0x2000
	s_nop 0
	global_load_lds_dwordx4 v[142:143], off
	s_waitcnt vmcnt(6)
	s_barrier
	v_mfma_f32_16x16x32_bf16 v[54:57], v[232:235], v[188:191], v[54:57]
	v_mfma_f32_16x16x32_bf16 v[50:53], v[240:243], v[188:191], v[50:53]
	v_mfma_f32_16x16x32_bf16 v[38:41], v[232:235], v[196:199], v[38:41]
	v_mfma_f32_16x16x32_bf16 v[34:37], v[240:243], v[196:199], v[34:37]
	v_mfma_f32_16x16x32_bf16 v[22:25], v[232:235], v[216:219], v[22:25]
	v_mfma_f32_16x16x32_bf16 v[18:21], v[240:243], v[216:219], v[18:21]
	v_mfma_f32_16x16x32_bf16 v[6:9], v[232:235], v[224:227], v[6:9]
	v_mfma_f32_16x16x32_bf16 v[2:5], v[240:243], v[224:227], v[2:5]
	v_mfma_f32_16x16x32_bf16 v[54:57], v[236:239], v[192:195], v[54:57]
	v_mfma_f32_16x16x32_bf16 v[50:53], v[244:247], v[192:195], v[50:53]
	v_mfma_f32_16x16x32_bf16 v[38:41], v[236:239], v[200:203], v[38:41]
	v_mfma_f32_16x16x32_bf16 v[34:37], v[244:247], v[200:203], v[34:37]
	v_mfma_f32_16x16x32_bf16 v[22:25], v[236:239], v[220:223], v[22:25]
	v_mfma_f32_16x16x32_bf16 v[18:21], v[244:247], v[220:223], v[18:21]
	v_mfma_f32_16x16x32_bf16 v[6:9], v[236:239], v[228:231], v[6:9]
	v_mfma_f32_16x16x32_bf16 v[2:5], v[244:247], v[228:231], v[2:5]
	s_add_i32 s44, s44, 2
	s_add_u32 s25, s25, 0x100
	s_addc_u32 s46, s46, 0
	s_cmp_gt_u32 s44, 5
	s_mov_b64 s[78:79], s[6:7]
	s_barrier
	s_cbranch_scc0 .LBB0_433
	v_lshl_add_u32 v144, s41, 8, v152
	v_ashrrev_i32_e32 v145, 31, v144
	v_lshl_add_u64 v[146:147], v[144:145], 2, s[50:51]
	global_load_dword v216, v[146:147], off
	global_load_dword v217, v[146:147], off offset:64
	global_load_dword v218, v[146:147], off offset:128
	global_load_dword v219, v[146:147], off offset:192
	global_load_dword v220, v[146:147], off offset:512
	global_load_dword v221, v[146:147], off offset:576
	global_load_dword v222, v[146:147], off offset:640
	global_load_dword v223, v[146:147], off offset:704
	v_lshl_or_b32 v142, s40, 8, v154
	s_mov_b32 s2, 0x2aaaaaab
	v_mul_hi_i32 v143, v142, s2
	v_lshlrev_b64 v[148:149], 8, v[144:145]
	v_lshrrev_b32_e32 v145, 31, v143
	v_lshrrev_b32_e32 v143, 5, v143
	v_add_u32_e32 v143, v143, v145
	s_movk_i32 s2, 0xc0
	v_mul_lo_u32 v143, v143, s2
	v_sub_u32_e32 v143, v142, v143
	s_movk_i32 s2, 0x7f
	v_cmp_lt_i32_e32 vcc, s2, v143
	v_add_u32_e32 v143, 0xffffff80, v143
	v_lshl_add_u64 v[148:149], s[20:21], 0, v[148:149]
	s_waitcnt vmcnt(0)
	v_mov_b32_e32 v0, v216
	v_mul_f32_e32 v150, 0x3dd53b94, v0
	v_pk_mul_f32 v[128:129], v[128:129], v[150:151] op_sel_hi:[1,0]
	v_pk_mul_f32 v[126:127], v[126:127], v[150:151] op_sel_hi:[1,0]
	v_pk_mul_f32 v[124:125], v[124:125], v[150:151] op_sel_hi:[1,0]
	v_pk_mul_f32 v[122:123], v[122:123], v[150:151] op_sel_hi:[1,0]
	v_lshrrev_b32_e32 v0, 1, v143
	s_and_saveexec_b64 s[6:7], vcc
	s_cbranch_execz .LBB0_436
	v_lshl_add_u64 v[160:161], v[0:1], 3, v[148:149]
	v_mov_b32_e32 v234, 0x1000
	v_mov_b32_e32 v235, 0
	v_lshl_add_u64 v[232:233], v[160:161], 0, v[234:235]
	global_load_dwordx4 v[156:159], v[160:161], off offset:16
	s_nop 0
	global_load_dwordx4 v[160:163], v[160:161], off
	global_load_dwordx4 v[224:227], v[232:233], off offset:16
	global_load_dwordx4 v[228:231], v[232:233], off
	s_waitcnt vmcnt(2)
	v_pk_mul_f32 v[190:191], v[122:123], v[156:157] op_sel:[1,1] op_sel_hi:[0,1]
	v_pk_mul_f32 v[188:189], v[126:127], v[160:161] op_sel:[1,1] op_sel_hi:[0,1]
	v_pk_mul_f32 v[164:165], v[126:127], v[160:161]
	v_pk_fma_f32 v[126:127], v[126:127], v[160:161], v[188:189] op_sel_hi:[1,0,1]
	s_nop 0
	v_mul_f32_e32 v126, v129, v163
	v_pk_fma_f32 v[160:161], v[128:129], v[162:163], v[126:127] op_sel_hi:[1,1,0] neg_lo:[0,0,1] neg_hi:[0,0,1]
	v_mul_f32_e32 v126, v128, v163
	v_pk_fma_f32 v[162:163], v[128:129], v[162:163], v[126:127] op_sel:[1,0,0] op_sel_hi:[0,1,0]
	v_pk_mul_f32 v[128:129], v[122:123], v[156:157]
	v_pk_fma_f32 v[122:123], v[122:123], v[156:157], v[190:191] op_sel_hi:[1,0,1]
	v_sub_f32_e32 v126, v164, v188
	v_mul_f32_e32 v122, v125, v159
	v_pk_fma_f32 v[156:157], v[124:125], v[158:159], v[122:123] op_sel_hi:[1,1,0] neg_lo:[0,0,1] neg_hi:[0,0,1]
	v_mul_f32_e32 v122, v124, v159
	v_pk_fma_f32 v[158:159], v[124:125], v[158:159], v[122:123] op_sel:[1,0,0] op_sel_hi:[0,1,0]
	v_sub_f32_e32 v122, v128, v190
	v_mov_b32_e32 v128, v160
	v_mov_b32_e32 v129, v162
	v_mov_b32_e32 v124, v156
	v_mov_b32_e32 v125, v158
.LBB0_436:
	s_or_b64 exec, exec, s[6:7]
	v_cvt_pk_bf16_f32 v126, v126, v127
	v_cvt_pk_bf16_f32 v127, v128, v129
	v_cvt_pk_bf16_f32 v128, v122, v123
	v_mov_b64_e32 v[122:123], s[52:53]
	v_mad_i64_i32 v[122:123], s[6:7], v144, s31, v[122:123]
	v_ashrrev_i32_e32 v143, 31, v142
	v_cvt_pk_bf16_f32 v129, v124, v125
	v_lshl_add_u64 v[122:123], v[142:143], 1, v[122:123]
	v_mov_b32_e32 v151, v150
	global_store_dwordx4 v[122:123], v[126:129], off
	s_mov_b32 s2, 0x2aaaaaab
	v_pk_mul_f32 v[118:119], v[118:119], v[150:151]
	v_or_b32_e32 v128, 0x80, v142
	v_mov_b32_e32 v126, v150
	v_mov_b32_e32 v127, v150
	v_pk_mul_f32 v[124:125], v[120:121], v[126:127]
	v_pk_mul_f32 v[120:121], v[116:117], v[126:127]
	v_pk_mul_f32 v[116:117], v[114:115], v[150:151]
	v_mul_hi_i32 v114, v128, s2
	v_lshrrev_b32_e32 v115, 31, v114
	v_lshrrev_b32_e32 v114, 5, v114
	v_add_u32_e32 v114, v114, v115
	s_movk_i32 s2, 0xc0
	v_mul_lo_u32 v114, v114, s2
	v_sub_u32_e32 v114, v128, v114
	s_movk_i32 s2, 0x7f
	v_cmp_lt_i32_e64 s[6:7], s2, v114
	v_add_u32_e32 v114, 0xffffff80, v114
	v_lshrrev_b32_e32 v114, 1, v114
	s_and_saveexec_b64 s[78:79], s[6:7]
	s_cbranch_execz .LBB0_438
	v_mov_b32_e32 v115, v1
	v_lshl_add_u64 v[148:149], v[114:115], 3, v[148:149]
	v_mov_b32_e32 v234, 0x1000
	v_mov_b32_e32 v235, 0
	v_lshl_add_u64 v[232:233], v[148:149], 0, v[234:235]
	global_load_dwordx4 v[126:129], v[148:149], off offset:16
	s_nop 0
	global_load_dwordx4 v[148:151], v[148:149], off
	global_load_dwordx4 v[224:227], v[232:233], off offset:16
	global_load_dwordx4 v[228:231], v[232:233], off
	s_waitcnt vmcnt(2)
	v_pk_mul_f32 v[160:161], v[116:117], v[126:127] op_sel:[1,1] op_sel_hi:[0,1]
	v_pk_mul_f32 v[158:159], v[118:119], v[148:149] op_sel:[1,1] op_sel_hi:[0,1]
	v_pk_mul_f32 v[156:157], v[118:119], v[148:149]
	v_pk_fma_f32 v[118:119], v[118:119], v[148:149], v[158:159] op_sel_hi:[1,0,1]
	s_nop 0
	v_mul_f32_e32 v118, v125, v151
	v_pk_fma_f32 v[148:149], v[124:125], v[150:151], v[118:119] op_sel_hi:[1,1,0] neg_lo:[0,0,1] neg_hi:[0,0,1]
	v_mul_f32_e32 v118, v124, v151
	v_pk_fma_f32 v[150:151], v[124:125], v[150:151], v[118:119] op_sel:[1,0,0] op_sel_hi:[0,1,0]
	v_pk_mul_f32 v[124:125], v[116:117], v[126:127]
	v_pk_fma_f32 v[116:117], v[116:117], v[126:127], v[160:161] op_sel_hi:[1,0,1]
	v_sub_f32_e32 v118, v156, v158
	v_mul_f32_e32 v116, v121, v129
	v_pk_fma_f32 v[126:127], v[120:121], v[128:129], v[116:117] op_sel_hi:[1,1,0] neg_lo:[0,0,1] neg_hi:[0,0,1]
	v_mul_f32_e32 v116, v120, v129
	v_pk_fma_f32 v[128:129], v[120:121], v[128:129], v[116:117] op_sel:[1,0,0] op_sel_hi:[0,1,0]
	v_sub_f32_e32 v116, v124, v160
	v_mov_b32_e32 v124, v148
	v_mov_b32_e32 v125, v150
	v_mov_b32_e32 v120, v126
	v_mov_b32_e32 v121, v128
.LBB0_438:
	s_or_b64 exec, exec, s[78:79]
	v_cvt_pk_bf16_f32 v126, v118, v119
	v_or_b32_e32 v118, 16, v144
	v_cvt_pk_bf16_f32 v127, v124, v125
	v_cvt_pk_bf16_f32 v128, v116, v117
	v_cvt_pk_bf16_f32 v129, v120, v121
	v_ashrrev_i32_e32 v119, 31, v118
	global_store_dwordx4 v[122:123], v[126:129], off offset:256
	v_lshl_add_u64 v[116:117], v[118:119], 2, s[50:51]
	s_nop 1
	v_mov_b32_e32 v115, v217
	v_lshlrev_b64 v[122:123], 8, v[118:119]
	s_nop 0
	v_mul_f32_e32 v116, 0x3dd53b94, v115
	v_pk_mul_f32 v[120:121], v[112:113], v[116:117] op_sel_hi:[1,0]
	v_pk_mul_f32 v[110:111], v[110:111], v[116:117] op_sel_hi:[1,0]
	v_pk_mul_f32 v[112:113], v[108:109], v[116:117] op_sel_hi:[1,0]
	v_pk_mul_f32 v[108:109], v[106:107], v[116:117] op_sel_hi:[1,0]
	v_lshl_add_u64 v[106:107], s[20:21], 0, v[122:123]
	s_and_saveexec_b64 s[78:79], vcc
	s_cbranch_execz .LBB0_440
	s_waitcnt vmcnt(2)
	v_mov_b32_e32 v122, v224
	v_mov_b32_e32 v123, v225
	v_mov_b32_e32 v124, v226
	v_mov_b32_e32 v125, v227
	v_mov_b32_e32 v126, v228
	v_mov_b32_e32 v127, v229
	v_mov_b32_e32 v128, v230
	v_mov_b32_e32 v129, v231
	v_lshl_add_u64 v[232:233], v[232:233], 0, v[234:235]
	global_load_dwordx4 v[224:227], v[232:233], off offset:16
	global_load_dwordx4 v[228:231], v[232:233], off
	v_pk_mul_f32 v[156:157], v[108:109], v[122:123] op_sel:[1,1] op_sel_hi:[0,1]
	v_pk_mul_f32 v[150:151], v[110:111], v[126:127] op_sel:[1,1] op_sel_hi:[0,1]
	v_pk_mul_f32 v[148:149], v[110:111], v[126:127]
	v_pk_fma_f32 v[110:111], v[110:111], v[126:127], v[150:151] op_sel_hi:[1,0,1]
	s_nop 0
	v_mul_f32_e32 v110, v121, v129
	v_pk_fma_f32 v[126:127], v[120:121], v[128:129], v[110:111] op_sel_hi:[1,1,0] neg_lo:[0,0,1] neg_hi:[0,0,1]
	v_mul_f32_e32 v110, v120, v129
	v_pk_fma_f32 v[128:129], v[120:121], v[128:129], v[110:111] op_sel:[1,0,0] op_sel_hi:[0,1,0]
	v_pk_mul_f32 v[120:121], v[108:109], v[122:123]
	v_pk_fma_f32 v[108:109], v[108:109], v[122:123], v[156:157] op_sel_hi:[1,0,1]
	v_sub_f32_e32 v110, v148, v150
	v_mul_f32_e32 v108, v113, v125
	v_pk_fma_f32 v[122:123], v[112:113], v[124:125], v[108:109] op_sel_hi:[1,1,0] neg_lo:[0,0,1] neg_hi:[0,0,1]
	v_mul_f32_e32 v108, v112, v125
	v_pk_fma_f32 v[124:125], v[112:113], v[124:125], v[108:109] op_sel:[1,0,0] op_sel_hi:[0,1,0]
	v_sub_f32_e32 v108, v120, v156
	v_mov_b32_e32 v120, v126
	v_mov_b32_e32 v121, v128
	v_mov_b32_e32 v112, v122
	v_mov_b32_e32 v113, v124
.LBB0_440:
	s_or_b64 exec, exec, s[78:79]
	v_cvt_pk_bf16_f32 v124, v108, v109
	v_mov_b64_e32 v[108:109], s[52:53]
	v_mov_b32_e32 v117, v116
	v_cvt_pk_bf16_f32 v122, v110, v111
	v_mad_i64_i32 v[108:109], s[24:25], v118, s31, v[108:109]
	v_mov_b32_e32 v110, v116
	v_mov_b32_e32 v111, v116
	v_cvt_pk_bf16_f32 v123, v120, v121
	v_cvt_pk_bf16_f32 v125, v112, v113
	v_lshl_add_u64 v[108:109], v[142:143], 1, v[108:109]
	v_pk_mul_f32 v[104:105], v[104:105], v[110:111]
	v_pk_mul_f32 v[102:103], v[102:103], v[116:117]
	v_pk_mul_f32 v[100:101], v[100:101], v[110:111]
	v_pk_mul_f32 v[98:99], v[98:99], v[116:117]
	global_store_dwordx4 v[108:109], v[122:125], off
	s_and_saveexec_b64 s[78:79], s[6:7]
	s_cbranch_execz .LBB0_442
	v_mov_b32_e32 v115, v1
	s_waitcnt vmcnt(2)
	v_mov_b32_e32 v110, v224
	v_mov_b32_e32 v111, v225
	v_mov_b32_e32 v112, v226
	v_mov_b32_e32 v113, v227
	v_mov_b32_e32 v116, v228
	v_mov_b32_e32 v117, v229
	v_mov_b32_e32 v118, v230
	v_mov_b32_e32 v119, v231
	v_lshl_add_u64 v[232:233], v[232:233], 0, v[234:235]
	global_load_dwordx4 v[224:227], v[232:233], off offset:16
	global_load_dwordx4 v[228:231], v[232:233], off
	v_pk_mul_f32 v[122:123], v[98:99], v[110:111] op_sel:[1,1] op_sel_hi:[0,1]
	v_pk_mul_f32 v[120:121], v[102:103], v[116:117] op_sel:[1,1] op_sel_hi:[0,1]
	v_pk_mul_f32 v[106:107], v[102:103], v[116:117]
	v_pk_fma_f32 v[102:103], v[102:103], v[116:117], v[120:121] op_sel_hi:[1,0,1]
	s_nop 0
	v_mul_f32_e32 v102, v105, v119
	v_pk_fma_f32 v[116:117], v[104:105], v[118:119], v[102:103] op_sel_hi:[1,1,0] neg_lo:[0,0,1] neg_hi:[0,0,1]
	v_mul_f32_e32 v102, v104, v119
	v_pk_fma_f32 v[118:119], v[104:105], v[118:119], v[102:103] op_sel:[1,0,0] op_sel_hi:[0,1,0]
	v_pk_mul_f32 v[104:105], v[98:99], v[110:111]
	v_pk_fma_f32 v[98:99], v[98:99], v[110:111], v[122:123] op_sel_hi:[1,0,1]
	v_sub_f32_e32 v102, v106, v120
	v_mul_f32_e32 v98, v101, v113
	v_pk_fma_f32 v[110:111], v[100:101], v[112:113], v[98:99] op_sel_hi:[1,1,0] neg_lo:[0,0,1] neg_hi:[0,0,1]
	v_mul_f32_e32 v98, v100, v113
	v_pk_fma_f32 v[112:113], v[100:101], v[112:113], v[98:99] op_sel:[1,0,0] op_sel_hi:[0,1,0]
	v_sub_f32_e32 v98, v104, v122
	v_mov_b32_e32 v104, v116
	v_mov_b32_e32 v105, v118
	v_mov_b32_e32 v100, v110
	v_mov_b32_e32 v101, v112
.LBB0_442:
	s_or_b64 exec, exec, s[78:79]
	v_cvt_pk_bf16_f32 v102, v102, v103
	v_cvt_pk_bf16_f32 v103, v104, v105
	v_cvt_pk_bf16_f32 v105, v100, v101
	v_or_b32_e32 v100, 32, v144
	v_cvt_pk_bf16_f32 v104, v98, v99
	v_ashrrev_i32_e32 v101, 31, v100
	global_store_dwordx4 v[108:109], v[102:105], off offset:256
	v_lshl_add_u64 v[98:99], v[100:101], 2, s[50:51]
	s_nop 1
	v_mov_b32_e32 v98, v218
	v_lshlrev_b64 v[104:105], 8, v[100:101]
	s_nop 0
	v_mul_f32_e32 v98, 0x3dd53b94, v98
	v_pk_mul_f32 v[102:103], v[96:97], v[98:99] op_sel_hi:[1,0]
	v_pk_mul_f32 v[94:95], v[94:95], v[98:99] op_sel_hi:[1,0]
	v_pk_mul_f32 v[96:97], v[92:93], v[98:99] op_sel_hi:[1,0]
	v_pk_mul_f32 v[92:93], v[90:91], v[98:99] op_sel_hi:[1,0]
	v_lshl_add_u64 v[90:91], s[20:21], 0, v[104:105]
	s_and_saveexec_b64 s[78:79], vcc
	s_cbranch_execz .LBB0_444
	s_waitcnt vmcnt(2)
	v_mov_b32_e32 v104, v224
	v_mov_b32_e32 v105, v225
	v_mov_b32_e32 v106, v226
	v_mov_b32_e32 v107, v227
	v_mov_b32_e32 v108, v228
	v_mov_b32_e32 v109, v229
	v_mov_b32_e32 v110, v230
	v_mov_b32_e32 v111, v231
	v_lshl_add_u64 v[232:233], v[232:233], 0, v[234:235]
	global_load_dwordx4 v[224:227], v[232:233], off offset:16
	global_load_dwordx4 v[228:231], v[232:233], off
	v_pk_mul_f32 v[118:119], v[92:93], v[104:105] op_sel:[1,1] op_sel_hi:[0,1]
	v_pk_mul_f32 v[116:117], v[94:95], v[108:109] op_sel:[1,1] op_sel_hi:[0,1]
	v_pk_mul_f32 v[112:113], v[94:95], v[108:109]
	v_pk_fma_f32 v[94:95], v[94:95], v[108:109], v[116:117] op_sel_hi:[1,0,1]
	s_nop 0
	v_mul_f32_e32 v94, v103, v111
	v_pk_fma_f32 v[108:109], v[102:103], v[110:111], v[94:95] op_sel_hi:[1,1,0] neg_lo:[0,0,1] neg_hi:[0,0,1]
	v_mul_f32_e32 v94, v102, v111
	v_pk_fma_f32 v[110:111], v[102:103], v[110:111], v[94:95] op_sel:[1,0,0] op_sel_hi:[0,1,0]
	v_pk_mul_f32 v[102:103], v[92:93], v[104:105]
	v_pk_fma_f32 v[92:93], v[92:93], v[104:105], v[118:119] op_sel_hi:[1,0,1]
	v_sub_f32_e32 v94, v112, v116
	v_mul_f32_e32 v92, v97, v107
	v_pk_fma_f32 v[104:105], v[96:97], v[106:107], v[92:93] op_sel_hi:[1,1,0] neg_lo:[0,0,1] neg_hi:[0,0,1]
	v_mul_f32_e32 v92, v96, v107
	v_pk_fma_f32 v[106:107], v[96:97], v[106:107], v[92:93] op_sel:[1,0,0] op_sel_hi:[0,1,0]
	v_sub_f32_e32 v92, v102, v118
	v_mov_b32_e32 v102, v108
	v_mov_b32_e32 v103, v110
	v_mov_b32_e32 v96, v104
	v_mov_b32_e32 v97, v106
.LBB0_444:
	s_or_b64 exec, exec, s[78:79]
	v_cvt_pk_bf16_f32 v106, v92, v93
	v_mov_b64_e32 v[92:93], s[52:53]
	v_mov_b32_e32 v99, v98
	v_cvt_pk_bf16_f32 v104, v94, v95
	v_mad_i64_i32 v[92:93], s[24:25], v100, s31, v[92:93]
	v_mov_b32_e32 v94, v98
	v_mov_b32_e32 v95, v98
	v_cvt_pk_bf16_f32 v105, v102, v103
	v_cvt_pk_bf16_f32 v107, v96, v97
	v_lshl_add_u64 v[92:93], v[142:143], 1, v[92:93]
	v_pk_mul_f32 v[88:89], v[88:89], v[94:95]
	v_pk_mul_f32 v[86:87], v[86:87], v[98:99]
	v_pk_mul_f32 v[84:85], v[84:85], v[94:95]
	v_pk_mul_f32 v[82:83], v[82:83], v[98:99]
	global_store_dwordx4 v[92:93], v[104:107], off
	s_and_saveexec_b64 s[78:79], s[6:7]
	s_cbranch_execz .LBB0_446
	v_mov_b32_e32 v115, v1
	s_waitcnt vmcnt(2)
	v_mov_b32_e32 v94, v224
	v_mov_b32_e32 v95, v225
	v_mov_b32_e32 v96, v226
	v_mov_b32_e32 v97, v227
	v_mov_b32_e32 v98, v228
	v_mov_b32_e32 v99, v229
	v_mov_b32_e32 v100, v230
	v_mov_b32_e32 v101, v231
	v_lshl_add_u64 v[232:233], v[232:233], 0, v[234:235]
	global_load_dwordx4 v[224:227], v[232:233], off offset:16
	global_load_dwordx4 v[228:231], v[232:233], off
	v_pk_mul_f32 v[104:105], v[82:83], v[94:95] op_sel:[1,1] op_sel_hi:[0,1]
	v_pk_mul_f32 v[102:103], v[86:87], v[98:99] op_sel:[1,1] op_sel_hi:[0,1]
	v_pk_mul_f32 v[90:91], v[86:87], v[98:99]
	v_pk_fma_f32 v[86:87], v[86:87], v[98:99], v[102:103] op_sel_hi:[1,0,1]
	s_nop 0
	v_mul_f32_e32 v86, v89, v101
	v_pk_fma_f32 v[98:99], v[88:89], v[100:101], v[86:87] op_sel_hi:[1,1,0] neg_lo:[0,0,1] neg_hi:[0,0,1]
	v_mul_f32_e32 v86, v88, v101
	v_pk_fma_f32 v[100:101], v[88:89], v[100:101], v[86:87] op_sel:[1,0,0] op_sel_hi:[0,1,0]
	v_pk_mul_f32 v[88:89], v[82:83], v[94:95]
	v_pk_fma_f32 v[82:83], v[82:83], v[94:95], v[104:105] op_sel_hi:[1,0,1]
	v_sub_f32_e32 v86, v90, v102
	v_mul_f32_e32 v82, v85, v97
	v_pk_fma_f32 v[94:95], v[84:85], v[96:97], v[82:83] op_sel_hi:[1,1,0] neg_lo:[0,0,1] neg_hi:[0,0,1]
	v_mul_f32_e32 v82, v84, v97
	v_pk_fma_f32 v[96:97], v[84:85], v[96:97], v[82:83] op_sel:[1,0,0] op_sel_hi:[0,1,0]
	v_sub_f32_e32 v82, v88, v104
	v_mov_b32_e32 v88, v98
	v_mov_b32_e32 v89, v100
	v_mov_b32_e32 v84, v94
	v_mov_b32_e32 v85, v96
.LBB0_446:
	s_or_b64 exec, exec, s[78:79]
	v_cvt_pk_bf16_f32 v86, v86, v87
	v_cvt_pk_bf16_f32 v87, v88, v89
	v_cvt_pk_bf16_f32 v89, v84, v85
	v_or_b32_e32 v84, 48, v144
	v_cvt_pk_bf16_f32 v88, v82, v83
	v_ashrrev_i32_e32 v85, 31, v84
	global_store_dwordx4 v[92:93], v[86:89], off offset:256
	v_lshl_add_u64 v[82:83], v[84:85], 2, s[50:51]
	s_nop 1
	v_mov_b32_e32 v82, v219
	v_lshlrev_b64 v[88:89], 8, v[84:85]
	s_nop 0
	v_mul_f32_e32 v82, 0x3dd53b94, v82
	v_pk_mul_f32 v[86:87], v[80:81], v[82:83] op_sel_hi:[1,0]
	v_pk_mul_f32 v[78:79], v[78:79], v[82:83] op_sel_hi:[1,0]
	v_pk_mul_f32 v[80:81], v[76:77], v[82:83] op_sel_hi:[1,0]
	v_pk_mul_f32 v[76:77], v[74:75], v[82:83] op_sel_hi:[1,0]
	v_lshl_add_u64 v[74:75], s[20:21], 0, v[88:89]
	s_and_saveexec_b64 s[78:79], vcc
	s_cbranch_execz .LBB0_448
	s_waitcnt vmcnt(2)
	v_mov_b32_e32 v88, v224
	v_mov_b32_e32 v89, v225
	v_mov_b32_e32 v90, v226
	v_mov_b32_e32 v91, v227
	v_mov_b32_e32 v92, v228
	v_mov_b32_e32 v93, v229
	v_mov_b32_e32 v94, v230
	v_mov_b32_e32 v95, v231
	v_mov_b32_e32 v234, 0x5000
	v_lshl_add_u64 v[232:233], v[232:233], 0, v[234:235]
	global_load_dwordx4 v[224:227], v[232:233], off offset:16
	global_load_dwordx4 v[228:231], v[232:233], off
	v_pk_mul_f32 v[100:101], v[76:77], v[88:89] op_sel:[1,1] op_sel_hi:[0,1]
	v_pk_mul_f32 v[98:99], v[78:79], v[92:93] op_sel:[1,1] op_sel_hi:[0,1]
	v_pk_mul_f32 v[96:97], v[78:79], v[92:93]
	v_pk_fma_f32 v[78:79], v[78:79], v[92:93], v[98:99] op_sel_hi:[1,0,1]
	s_nop 0
	v_mul_f32_e32 v78, v87, v95
	v_pk_fma_f32 v[92:93], v[86:87], v[94:95], v[78:79] op_sel_hi:[1,1,0] neg_lo:[0,0,1] neg_hi:[0,0,1]
	v_mul_f32_e32 v78, v86, v95
	v_pk_fma_f32 v[94:95], v[86:87], v[94:95], v[78:79] op_sel:[1,0,0] op_sel_hi:[0,1,0]
	v_pk_mul_f32 v[86:87], v[76:77], v[88:89]
	v_pk_fma_f32 v[76:77], v[76:77], v[88:89], v[100:101] op_sel_hi:[1,0,1]
	v_sub_f32_e32 v78, v96, v98
	v_mul_f32_e32 v76, v81, v91
	v_pk_fma_f32 v[88:89], v[80:81], v[90:91], v[76:77] op_sel_hi:[1,1,0] neg_lo:[0,0,1] neg_hi:[0,0,1]
	v_mul_f32_e32 v76, v80, v91
	v_pk_fma_f32 v[90:91], v[80:81], v[90:91], v[76:77] op_sel:[1,0,0] op_sel_hi:[0,1,0]
	v_sub_f32_e32 v76, v86, v100
	v_mov_b32_e32 v86, v92
	v_mov_b32_e32 v87, v94
	v_mov_b32_e32 v80, v88
	v_mov_b32_e32 v81, v90
.LBB0_448:
	s_or_b64 exec, exec, s[78:79]
	v_cvt_pk_bf16_f32 v90, v76, v77
	v_mov_b64_e32 v[76:77], s[52:53]
	v_mov_b32_e32 v83, v82
	v_cvt_pk_bf16_f32 v88, v78, v79
	v_mad_i64_i32 v[76:77], s[24:25], v84, s31, v[76:77]
	v_mov_b32_e32 v78, v82
	v_mov_b32_e32 v79, v82
	v_cvt_pk_bf16_f32 v89, v86, v87
	v_cvt_pk_bf16_f32 v91, v80, v81
	v_lshl_add_u64 v[76:77], v[142:143], 1, v[76:77]
	v_pk_mul_f32 v[72:73], v[72:73], v[78:79]
	v_pk_mul_f32 v[70:71], v[70:71], v[82:83]
	v_pk_mul_f32 v[68:69], v[68:69], v[78:79]
	v_pk_mul_f32 v[66:67], v[66:67], v[82:83]
	global_store_dwordx4 v[76:77], v[88:91], off
	s_and_saveexec_b64 s[78:79], s[6:7]
	s_cbranch_execz .LBB0_450
	v_mov_b32_e32 v115, v1
	s_waitcnt vmcnt(2)
	v_mov_b32_e32 v78, v224
	v_mov_b32_e32 v79, v225
	v_mov_b32_e32 v80, v226
	v_mov_b32_e32 v81, v227
	v_mov_b32_e32 v82, v228
	v_mov_b32_e32 v83, v229
	v_mov_b32_e32 v84, v230
	v_mov_b32_e32 v85, v231
	v_mov_b32_e32 v234, 0x5000
	v_lshl_add_u64 v[232:233], v[232:233], 0, v[234:235]
	global_load_dwordx4 v[224:227], v[232:233], off offset:16
	global_load_dwordx4 v[228:231], v[232:233], off
	v_pk_mul_f32 v[88:89], v[66:67], v[78:79] op_sel:[1,1] op_sel_hi:[0,1]
	v_pk_mul_f32 v[86:87], v[70:71], v[82:83] op_sel:[1,1] op_sel_hi:[0,1]
	v_pk_mul_f32 v[74:75], v[70:71], v[82:83]
	v_pk_fma_f32 v[70:71], v[70:71], v[82:83], v[86:87] op_sel_hi:[1,0,1]
	s_nop 0
	v_mul_f32_e32 v70, v73, v85
	v_pk_fma_f32 v[82:83], v[72:73], v[84:85], v[70:71] op_sel_hi:[1,1,0] neg_lo:[0,0,1] neg_hi:[0,0,1]
	v_mul_f32_e32 v70, v72, v85
	v_pk_fma_f32 v[84:85], v[72:73], v[84:85], v[70:71] op_sel:[1,0,0] op_sel_hi:[0,1,0]
	v_pk_mul_f32 v[72:73], v[66:67], v[78:79]
	v_pk_fma_f32 v[66:67], v[66:67], v[78:79], v[88:89] op_sel_hi:[1,0,1]
	v_sub_f32_e32 v70, v74, v86
	v_mul_f32_e32 v66, v69, v81
	v_pk_fma_f32 v[78:79], v[68:69], v[80:81], v[66:67] op_sel_hi:[1,1,0] neg_lo:[0,0,1] neg_hi:[0,0,1]
	v_mul_f32_e32 v66, v68, v81
	v_pk_fma_f32 v[80:81], v[68:69], v[80:81], v[66:67] op_sel:[1,0,0] op_sel_hi:[0,1,0]
	v_sub_f32_e32 v66, v72, v88
	v_mov_b32_e32 v72, v82
	v_mov_b32_e32 v73, v84
	v_mov_b32_e32 v68, v78
	v_mov_b32_e32 v69, v80
.LBB0_450:
	s_or_b64 exec, exec, s[78:79]
	v_cvt_pk_bf16_f32 v70, v70, v71
	v_cvt_pk_bf16_f32 v71, v72, v73
	v_cvt_pk_bf16_f32 v72, v66, v67
	v_cvt_pk_bf16_f32 v73, v68, v69
	global_store_dwordx4 v[76:77], v[70:73], off offset:256
	s_nop 1
	v_mov_b32_e32 v66, v220
	v_add_u32_e32 v68, 0x80, v144
	v_ashrrev_i32_e32 v69, 31, v68
	v_lshlrev_b64 v[72:73], 8, v[68:69]
	s_nop 0
	v_mul_f32_e32 v66, 0x3dd53b94, v66
	v_pk_mul_f32 v[70:71], v[64:65], v[66:67] op_sel_hi:[1,0]
	v_pk_mul_f32 v[62:63], v[62:63], v[66:67] op_sel_hi:[1,0]
	v_pk_mul_f32 v[64:65], v[60:61], v[66:67] op_sel_hi:[1,0]
	v_pk_mul_f32 v[60:61], v[58:59], v[66:67] op_sel_hi:[1,0]
	v_lshl_add_u64 v[58:59], s[20:21], 0, v[72:73]
	s_and_saveexec_b64 s[78:79], vcc
	s_cbranch_execz .LBB0_452
	s_waitcnt vmcnt(2)
	v_mov_b32_e32 v72, v224
	v_mov_b32_e32 v73, v225
	v_mov_b32_e32 v74, v226
	v_mov_b32_e32 v75, v227
	v_mov_b32_e32 v76, v228
	v_mov_b32_e32 v77, v229
	v_mov_b32_e32 v78, v230
	v_mov_b32_e32 v79, v231
	v_mov_b32_e32 v234, 0x1000
	v_lshl_add_u64 v[232:233], v[232:233], 0, v[234:235]
	global_load_dwordx4 v[224:227], v[232:233], off offset:16
	global_load_dwordx4 v[228:231], v[232:233], off
	v_pk_mul_f32 v[84:85], v[60:61], v[72:73] op_sel:[1,1] op_sel_hi:[0,1]
	v_pk_mul_f32 v[82:83], v[62:63], v[76:77] op_sel:[1,1] op_sel_hi:[0,1]
	v_pk_mul_f32 v[80:81], v[62:63], v[76:77]
	v_pk_fma_f32 v[62:63], v[62:63], v[76:77], v[82:83] op_sel_hi:[1,0,1]
	s_nop 0
	v_mul_f32_e32 v62, v71, v79
	v_pk_fma_f32 v[76:77], v[70:71], v[78:79], v[62:63] op_sel_hi:[1,1,0] neg_lo:[0,0,1] neg_hi:[0,0,1]
	v_mul_f32_e32 v62, v70, v79
	v_pk_fma_f32 v[78:79], v[70:71], v[78:79], v[62:63] op_sel:[1,0,0] op_sel_hi:[0,1,0]
	v_pk_mul_f32 v[70:71], v[60:61], v[72:73]
	v_pk_fma_f32 v[60:61], v[60:61], v[72:73], v[84:85] op_sel_hi:[1,0,1]
	v_sub_f32_e32 v62, v80, v82
	v_mul_f32_e32 v60, v65, v75
	v_pk_fma_f32 v[72:73], v[64:65], v[74:75], v[60:61] op_sel_hi:[1,1,0] neg_lo:[0,0,1] neg_hi:[0,0,1]
	v_mul_f32_e32 v60, v64, v75
	v_pk_fma_f32 v[74:75], v[64:65], v[74:75], v[60:61] op_sel:[1,0,0] op_sel_hi:[0,1,0]
	v_sub_f32_e32 v60, v70, v84
	v_mov_b32_e32 v70, v76
	v_mov_b32_e32 v71, v78
	v_mov_b32_e32 v64, v72
	v_mov_b32_e32 v65, v74
.LBB0_452:
	s_or_b64 exec, exec, s[78:79]
	v_cvt_pk_bf16_f32 v74, v60, v61
	v_mov_b64_e32 v[60:61], s[52:53]
	v_mov_b32_e32 v67, v66
	v_cvt_pk_bf16_f32 v72, v62, v63
	v_mad_i64_i32 v[60:61], s[24:25], v68, s31, v[60:61]
	v_mov_b32_e32 v62, v66
	v_mov_b32_e32 v63, v66
	v_cvt_pk_bf16_f32 v73, v70, v71
	v_cvt_pk_bf16_f32 v75, v64, v65
	v_lshl_add_u64 v[60:61], v[142:143], 1, v[60:61]
	v_pk_mul_f32 v[56:57], v[56:57], v[62:63]
	v_pk_mul_f32 v[54:55], v[54:55], v[66:67]
	v_pk_mul_f32 v[52:53], v[52:53], v[62:63]
	v_pk_mul_f32 v[50:51], v[50:51], v[66:67]
	global_store_dwordx4 v[60:61], v[72:75], off
	s_and_saveexec_b64 s[78:79], s[6:7]
	s_cbranch_execz .LBB0_454
	v_mov_b32_e32 v115, v1
	s_waitcnt vmcnt(2)
	v_mov_b32_e32 v62, v224
	v_mov_b32_e32 v63, v225
	v_mov_b32_e32 v64, v226
	v_mov_b32_e32 v65, v227
	v_mov_b32_e32 v66, v228
	v_mov_b32_e32 v67, v229
	v_mov_b32_e32 v68, v230
	v_mov_b32_e32 v69, v231
	v_mov_b32_e32 v234, 0x1000
	v_lshl_add_u64 v[232:233], v[232:233], 0, v[234:235]
	global_load_dwordx4 v[224:227], v[232:233], off offset:16
	global_load_dwordx4 v[228:231], v[232:233], off
	v_pk_mul_f32 v[72:73], v[50:51], v[62:63] op_sel:[1,1] op_sel_hi:[0,1]
	v_pk_mul_f32 v[70:71], v[54:55], v[66:67] op_sel:[1,1] op_sel_hi:[0,1]
	v_pk_mul_f32 v[58:59], v[54:55], v[66:67]
	v_pk_fma_f32 v[54:55], v[54:55], v[66:67], v[70:71] op_sel_hi:[1,0,1]
	s_nop 0
	v_mul_f32_e32 v54, v57, v69
	v_pk_fma_f32 v[66:67], v[56:57], v[68:69], v[54:55] op_sel_hi:[1,1,0] neg_lo:[0,0,1] neg_hi:[0,0,1]
	v_mul_f32_e32 v54, v56, v69
	v_pk_fma_f32 v[68:69], v[56:57], v[68:69], v[54:55] op_sel:[1,0,0] op_sel_hi:[0,1,0]
	v_pk_mul_f32 v[56:57], v[50:51], v[62:63]
	v_pk_fma_f32 v[50:51], v[50:51], v[62:63], v[72:73] op_sel_hi:[1,0,1]
	v_sub_f32_e32 v54, v58, v70
	v_mul_f32_e32 v50, v53, v65
	v_pk_fma_f32 v[62:63], v[52:53], v[64:65], v[50:51] op_sel_hi:[1,1,0] neg_lo:[0,0,1] neg_hi:[0,0,1]
	v_mul_f32_e32 v50, v52, v65
	v_pk_fma_f32 v[64:65], v[52:53], v[64:65], v[50:51] op_sel:[1,0,0] op_sel_hi:[0,1,0]
	v_sub_f32_e32 v50, v56, v72
	v_mov_b32_e32 v56, v66
	v_mov_b32_e32 v57, v68
	v_mov_b32_e32 v52, v62
	v_mov_b32_e32 v53, v64
.LBB0_454:
	s_or_b64 exec, exec, s[78:79]
	v_cvt_pk_bf16_f32 v54, v54, v55
	v_cvt_pk_bf16_f32 v55, v56, v57
	v_cvt_pk_bf16_f32 v56, v50, v51
	v_cvt_pk_bf16_f32 v57, v52, v53
	global_store_dwordx4 v[60:61], v[54:57], off offset:256
	s_nop 1
	v_mov_b32_e32 v50, v221
	v_add_u32_e32 v52, 0x90, v144
	v_ashrrev_i32_e32 v53, 31, v52
	v_lshlrev_b64 v[56:57], 8, v[52:53]
	s_nop 0
	v_mul_f32_e32 v50, 0x3dd53b94, v50
	v_pk_mul_f32 v[54:55], v[48:49], v[50:51] op_sel_hi:[1,0]
	v_pk_mul_f32 v[46:47], v[46:47], v[50:51] op_sel_hi:[1,0]
	v_pk_mul_f32 v[48:49], v[44:45], v[50:51] op_sel_hi:[1,0]
	v_pk_mul_f32 v[44:45], v[42:43], v[50:51] op_sel_hi:[1,0]
	v_lshl_add_u64 v[42:43], s[20:21], 0, v[56:57]
	s_and_saveexec_b64 s[78:79], vcc
	s_cbranch_execz .LBB0_456
	s_waitcnt vmcnt(2)
	v_mov_b32_e32 v56, v224
	v_mov_b32_e32 v57, v225
	v_mov_b32_e32 v58, v226
	v_mov_b32_e32 v59, v227
	v_mov_b32_e32 v60, v228
	v_mov_b32_e32 v61, v229
	v_mov_b32_e32 v62, v230
	v_mov_b32_e32 v63, v231
	v_lshl_add_u64 v[232:233], v[232:233], 0, v[234:235]
	global_load_dwordx4 v[224:227], v[232:233], off offset:16
	global_load_dwordx4 v[228:231], v[232:233], off
	v_pk_mul_f32 v[68:69], v[44:45], v[56:57] op_sel:[1,1] op_sel_hi:[0,1]
	v_pk_mul_f32 v[66:67], v[46:47], v[60:61] op_sel:[1,1] op_sel_hi:[0,1]
	v_pk_mul_f32 v[64:65], v[46:47], v[60:61]
	v_pk_fma_f32 v[46:47], v[46:47], v[60:61], v[66:67] op_sel_hi:[1,0,1]
	s_nop 0
	v_mul_f32_e32 v46, v55, v63
	v_pk_fma_f32 v[60:61], v[54:55], v[62:63], v[46:47] op_sel_hi:[1,1,0] neg_lo:[0,0,1] neg_hi:[0,0,1]
	v_mul_f32_e32 v46, v54, v63
	v_pk_fma_f32 v[62:63], v[54:55], v[62:63], v[46:47] op_sel:[1,0,0] op_sel_hi:[0,1,0]
	v_pk_mul_f32 v[54:55], v[44:45], v[56:57]
	v_pk_fma_f32 v[44:45], v[44:45], v[56:57], v[68:69] op_sel_hi:[1,0,1]
	v_sub_f32_e32 v46, v64, v66
	v_mul_f32_e32 v44, v49, v59
	v_pk_fma_f32 v[56:57], v[48:49], v[58:59], v[44:45] op_sel_hi:[1,1,0] neg_lo:[0,0,1] neg_hi:[0,0,1]
	v_mul_f32_e32 v44, v48, v59
	v_pk_fma_f32 v[58:59], v[48:49], v[58:59], v[44:45] op_sel:[1,0,0] op_sel_hi:[0,1,0]
	v_sub_f32_e32 v44, v54, v68
	v_mov_b32_e32 v54, v60
	v_mov_b32_e32 v55, v62
	v_mov_b32_e32 v48, v56
	v_mov_b32_e32 v49, v58
.LBB0_456:
	s_or_b64 exec, exec, s[78:79]
	v_cvt_pk_bf16_f32 v58, v44, v45
	v_mov_b64_e32 v[44:45], s[52:53]
	v_mov_b32_e32 v51, v50
	v_cvt_pk_bf16_f32 v56, v46, v47
	v_mad_i64_i32 v[44:45], s[24:25], v52, s31, v[44:45]
	v_mov_b32_e32 v46, v50
	v_mov_b32_e32 v47, v50
	v_cvt_pk_bf16_f32 v57, v54, v55
	v_cvt_pk_bf16_f32 v59, v48, v49
	v_lshl_add_u64 v[44:45], v[142:143], 1, v[44:45]
	v_pk_mul_f32 v[40:41], v[40:41], v[46:47]
	v_pk_mul_f32 v[38:39], v[38:39], v[50:51]
	v_pk_mul_f32 v[36:37], v[36:37], v[46:47]
	v_pk_mul_f32 v[34:35], v[34:35], v[50:51]
	global_store_dwordx4 v[44:45], v[56:59], off
	s_and_saveexec_b64 s[78:79], s[6:7]
	s_cbranch_execz .LBB0_458
	v_mov_b32_e32 v115, v1
	s_waitcnt vmcnt(2)
	v_mov_b32_e32 v46, v224
	v_mov_b32_e32 v47, v225
	v_mov_b32_e32 v48, v226
	v_mov_b32_e32 v49, v227
	v_mov_b32_e32 v50, v228
	v_mov_b32_e32 v51, v229
	v_mov_b32_e32 v52, v230
	v_mov_b32_e32 v53, v231
	v_lshl_add_u64 v[232:233], v[232:233], 0, v[234:235]
	global_load_dwordx4 v[224:227], v[232:233], off offset:16
	global_load_dwordx4 v[228:231], v[232:233], off
	v_pk_mul_f32 v[56:57], v[34:35], v[46:47] op_sel:[1,1] op_sel_hi:[0,1]
	v_pk_mul_f32 v[54:55], v[38:39], v[50:51] op_sel:[1,1] op_sel_hi:[0,1]
	v_pk_mul_f32 v[42:43], v[38:39], v[50:51]
	v_pk_fma_f32 v[38:39], v[38:39], v[50:51], v[54:55] op_sel_hi:[1,0,1]
	s_nop 0
	v_mul_f32_e32 v38, v41, v53
	v_pk_fma_f32 v[50:51], v[40:41], v[52:53], v[38:39] op_sel_hi:[1,1,0] neg_lo:[0,0,1] neg_hi:[0,0,1]
	v_mul_f32_e32 v38, v40, v53
	v_pk_fma_f32 v[52:53], v[40:41], v[52:53], v[38:39] op_sel:[1,0,0] op_sel_hi:[0,1,0]
	v_pk_mul_f32 v[40:41], v[34:35], v[46:47]
	v_pk_fma_f32 v[34:35], v[34:35], v[46:47], v[56:57] op_sel_hi:[1,0,1]
	v_sub_f32_e32 v38, v42, v54
	v_mul_f32_e32 v34, v37, v49
	v_pk_fma_f32 v[46:47], v[36:37], v[48:49], v[34:35] op_sel_hi:[1,1,0] neg_lo:[0,0,1] neg_hi:[0,0,1]
	v_mul_f32_e32 v34, v36, v49
	v_pk_fma_f32 v[48:49], v[36:37], v[48:49], v[34:35] op_sel:[1,0,0] op_sel_hi:[0,1,0]
	v_sub_f32_e32 v34, v40, v56
	v_mov_b32_e32 v40, v50
	v_mov_b32_e32 v41, v52
	v_mov_b32_e32 v36, v46
	v_mov_b32_e32 v37, v48
.LBB0_458:
	s_or_b64 exec, exec, s[78:79]
	v_cvt_pk_bf16_f32 v38, v38, v39
	v_cvt_pk_bf16_f32 v39, v40, v41
	v_cvt_pk_bf16_f32 v40, v34, v35
	v_cvt_pk_bf16_f32 v41, v36, v37
	global_store_dwordx4 v[44:45], v[38:41], off offset:256
	s_nop 1
	v_mov_b32_e32 v34, v222
	v_add_u32_e32 v36, 0xa0, v144
	v_ashrrev_i32_e32 v37, 31, v36
	v_lshlrev_b64 v[40:41], 8, v[36:37]
	s_nop 0
	v_mul_f32_e32 v34, 0x3dd53b94, v34
	v_pk_mul_f32 v[38:39], v[32:33], v[34:35] op_sel_hi:[1,0]
	v_pk_mul_f32 v[30:31], v[30:31], v[34:35] op_sel_hi:[1,0]
	v_pk_mul_f32 v[32:33], v[28:29], v[34:35] op_sel_hi:[1,0]
	v_pk_mul_f32 v[28:29], v[26:27], v[34:35] op_sel_hi:[1,0]
	v_lshl_add_u64 v[26:27], s[20:21], 0, v[40:41]
	s_and_saveexec_b64 s[78:79], vcc
	s_cbranch_execz .LBB0_460
	s_waitcnt vmcnt(2)
	v_mov_b32_e32 v40, v224
	v_mov_b32_e32 v41, v225
	v_mov_b32_e32 v42, v226
	v_mov_b32_e32 v43, v227
	v_mov_b32_e32 v44, v228
	v_mov_b32_e32 v45, v229
	v_mov_b32_e32 v46, v230
	v_mov_b32_e32 v47, v231
	v_lshl_add_u64 v[232:233], v[232:233], 0, v[234:235]
	global_load_dwordx4 v[224:227], v[232:233], off offset:16
	global_load_dwordx4 v[228:231], v[232:233], off
	v_pk_mul_f32 v[52:53], v[28:29], v[40:41] op_sel:[1,1] op_sel_hi:[0,1]
	v_pk_mul_f32 v[50:51], v[30:31], v[44:45] op_sel:[1,1] op_sel_hi:[0,1]
	v_pk_mul_f32 v[48:49], v[30:31], v[44:45]
	v_pk_fma_f32 v[30:31], v[30:31], v[44:45], v[50:51] op_sel_hi:[1,0,1]
	s_nop 0
	v_mul_f32_e32 v30, v39, v47
	v_pk_fma_f32 v[44:45], v[38:39], v[46:47], v[30:31] op_sel_hi:[1,1,0] neg_lo:[0,0,1] neg_hi:[0,0,1]
	v_mul_f32_e32 v30, v38, v47
	v_pk_fma_f32 v[46:47], v[38:39], v[46:47], v[30:31] op_sel:[1,0,0] op_sel_hi:[0,1,0]
	v_pk_mul_f32 v[38:39], v[28:29], v[40:41]
	v_pk_fma_f32 v[28:29], v[28:29], v[40:41], v[52:53] op_sel_hi:[1,0,1]
	v_sub_f32_e32 v30, v48, v50
	v_mul_f32_e32 v28, v33, v43
	v_pk_fma_f32 v[40:41], v[32:33], v[42:43], v[28:29] op_sel_hi:[1,1,0] neg_lo:[0,0,1] neg_hi:[0,0,1]
	v_mul_f32_e32 v28, v32, v43
	v_pk_fma_f32 v[42:43], v[32:33], v[42:43], v[28:29] op_sel:[1,0,0] op_sel_hi:[0,1,0]
	v_sub_f32_e32 v28, v38, v52
	v_mov_b32_e32 v38, v44
	v_mov_b32_e32 v39, v46
	v_mov_b32_e32 v32, v40
	v_mov_b32_e32 v33, v42
.LBB0_460:
	s_or_b64 exec, exec, s[78:79]
	v_cvt_pk_bf16_f32 v42, v28, v29
	v_mov_b64_e32 v[28:29], s[52:53]
	v_mov_b32_e32 v35, v34
	v_cvt_pk_bf16_f32 v40, v30, v31
	v_mad_i64_i32 v[28:29], s[24:25], v36, s31, v[28:29]
	v_mov_b32_e32 v30, v34
	v_mov_b32_e32 v31, v34
	v_cvt_pk_bf16_f32 v41, v38, v39
	v_cvt_pk_bf16_f32 v43, v32, v33
	v_lshl_add_u64 v[28:29], v[142:143], 1, v[28:29]
	v_pk_mul_f32 v[24:25], v[24:25], v[30:31]
	v_pk_mul_f32 v[22:23], v[22:23], v[34:35]
	v_pk_mul_f32 v[20:21], v[20:21], v[30:31]
	v_pk_mul_f32 v[18:19], v[18:19], v[34:35]
	global_store_dwordx4 v[28:29], v[40:43], off
	s_and_saveexec_b64 s[78:79], s[6:7]
	s_cbranch_execz .LBB0_462
	v_mov_b32_e32 v115, v1
	s_waitcnt vmcnt(2)
	v_mov_b32_e32 v30, v224
	v_mov_b32_e32 v31, v225
	v_mov_b32_e32 v32, v226
	v_mov_b32_e32 v33, v227
	v_mov_b32_e32 v34, v228
	v_mov_b32_e32 v35, v229
	v_mov_b32_e32 v36, v230
	v_mov_b32_e32 v37, v231
	v_lshl_add_u64 v[232:233], v[232:233], 0, v[234:235]
	global_load_dwordx4 v[224:227], v[232:233], off offset:16
	global_load_dwordx4 v[228:231], v[232:233], off
	v_pk_mul_f32 v[40:41], v[18:19], v[30:31] op_sel:[1,1] op_sel_hi:[0,1]
	v_pk_mul_f32 v[38:39], v[22:23], v[34:35] op_sel:[1,1] op_sel_hi:[0,1]
	v_pk_mul_f32 v[26:27], v[22:23], v[34:35]
	v_pk_fma_f32 v[22:23], v[22:23], v[34:35], v[38:39] op_sel_hi:[1,0,1]
	s_nop 0
	v_mul_f32_e32 v22, v25, v37
	v_pk_fma_f32 v[34:35], v[24:25], v[36:37], v[22:23] op_sel_hi:[1,1,0] neg_lo:[0,0,1] neg_hi:[0,0,1]
	v_mul_f32_e32 v22, v24, v37
	v_pk_fma_f32 v[36:37], v[24:25], v[36:37], v[22:23] op_sel:[1,0,0] op_sel_hi:[0,1,0]
	v_pk_mul_f32 v[24:25], v[18:19], v[30:31]
	v_pk_fma_f32 v[18:19], v[18:19], v[30:31], v[40:41] op_sel_hi:[1,0,1]
	v_sub_f32_e32 v22, v26, v38
	v_mul_f32_e32 v18, v21, v33
	v_pk_fma_f32 v[30:31], v[20:21], v[32:33], v[18:19] op_sel_hi:[1,1,0] neg_lo:[0,0,1] neg_hi:[0,0,1]
	v_mul_f32_e32 v18, v20, v33
	v_pk_fma_f32 v[32:33], v[20:21], v[32:33], v[18:19] op_sel:[1,0,0] op_sel_hi:[0,1,0]
	v_sub_f32_e32 v18, v24, v40
	v_mov_b32_e32 v24, v34
	v_mov_b32_e32 v25, v36
	v_mov_b32_e32 v20, v30
	v_mov_b32_e32 v21, v32
.LBB0_462:
	s_or_b64 exec, exec, s[78:79]
	v_cvt_pk_bf16_f32 v22, v22, v23
	v_cvt_pk_bf16_f32 v23, v24, v25
	v_cvt_pk_bf16_f32 v24, v18, v19
	v_cvt_pk_bf16_f32 v25, v20, v21
	global_store_dwordx4 v[28:29], v[22:25], off offset:256
	s_nop 1
	v_mov_b32_e32 v18, v223
	v_add_u32_e32 v20, 0xb0, v144
	v_ashrrev_i32_e32 v21, 31, v20
	v_lshlrev_b64 v[24:25], 8, v[20:21]
	s_nop 0
	v_mul_f32_e32 v18, 0x3dd53b94, v18
	v_pk_mul_f32 v[22:23], v[16:17], v[18:19] op_sel_hi:[1,0]
	v_pk_mul_f32 v[14:15], v[14:15], v[18:19] op_sel_hi:[1,0]
	v_pk_mul_f32 v[16:17], v[12:13], v[18:19] op_sel_hi:[1,0]
	v_pk_mul_f32 v[12:13], v[10:11], v[18:19] op_sel_hi:[1,0]
	v_lshl_add_u64 v[10:11], s[20:21], 0, v[24:25]
	s_and_saveexec_b64 s[78:79], vcc
	s_cbranch_execz .LBB0_464
	s_waitcnt vmcnt(2)
	v_mov_b32_e32 v24, v224
	v_mov_b32_e32 v25, v225
	v_mov_b32_e32 v26, v226
	v_mov_b32_e32 v27, v227
	v_mov_b32_e32 v28, v228
	v_mov_b32_e32 v29, v229
	v_mov_b32_e32 v30, v230
	v_mov_b32_e32 v31, v231
	v_pk_mul_f32 v[36:37], v[12:13], v[24:25] op_sel:[1,1] op_sel_hi:[0,1]
	v_pk_mul_f32 v[34:35], v[14:15], v[28:29] op_sel:[1,1] op_sel_hi:[0,1]
	v_mul_f32_e32 v0, v23, v31
	v_pk_mul_f32 v[32:33], v[14:15], v[28:29]
	v_pk_fma_f32 v[14:15], v[14:15], v[28:29], v[34:35] op_sel_hi:[1,0,1]
	v_pk_fma_f32 v[28:29], v[22:23], v[30:31], v[0:1] op_sel_hi:[1,1,0] neg_lo:[0,0,1] neg_hi:[0,0,1]
	v_mul_f32_e32 v0, v22, v31
	v_pk_fma_f32 v[30:31], v[22:23], v[30:31], v[0:1] op_sel:[1,0,0] op_sel_hi:[0,1,0]
	v_mul_f32_e32 v0, v17, v27
	v_pk_mul_f32 v[22:23], v[12:13], v[24:25]
	v_pk_fma_f32 v[12:13], v[12:13], v[24:25], v[36:37] op_sel_hi:[1,0,1]
	v_pk_fma_f32 v[24:25], v[16:17], v[26:27], v[0:1] op_sel_hi:[1,1,0] neg_lo:[0,0,1] neg_hi:[0,0,1]
	v_mul_f32_e32 v0, v16, v27
	v_pk_fma_f32 v[26:27], v[16:17], v[26:27], v[0:1] op_sel:[1,0,0] op_sel_hi:[0,1,0]
	v_sub_f32_e32 v14, v32, v34
	v_sub_f32_e32 v12, v22, v36
	v_mov_b32_e32 v22, v28
	v_mov_b32_e32 v23, v30
	v_mov_b32_e32 v16, v24
	v_mov_b32_e32 v17, v26
.LBB0_464:
	s_or_b64 exec, exec, s[78:79]
	v_cvt_pk_bf16_f32 v26, v12, v13
	v_mov_b64_e32 v[12:13], s[52:53]
	v_mov_b32_e32 v19, v18
	v_cvt_pk_bf16_f32 v24, v14, v15
	v_mad_i64_i32 v[12:13], s[24:25], v20, s31, v[12:13]
	v_mov_b32_e32 v14, v18
	v_mov_b32_e32 v15, v18
	v_cvt_pk_bf16_f32 v25, v22, v23
	v_cvt_pk_bf16_f32 v27, v16, v17
	v_lshl_add_u64 v[12:13], v[142:143], 1, v[12:13]
	v_pk_mul_f32 v[8:9], v[8:9], v[14:15]
	v_pk_mul_f32 v[6:7], v[6:7], v[18:19]
	v_pk_mul_f32 v[4:5], v[4:5], v[14:15]
	v_pk_mul_f32 v[2:3], v[2:3], v[18:19]
	global_store_dwordx4 v[12:13], v[24:27], off
	s_and_saveexec_b64 s[78:79], s[6:7]
	s_cbranch_execz .LBB0_427
	v_mov_b32_e32 v115, v1
	s_waitcnt vmcnt(2)
	v_mov_b32_e32 v14, v224
	v_mov_b32_e32 v15, v225
	v_mov_b32_e32 v16, v226
	v_mov_b32_e32 v17, v227
	v_mov_b32_e32 v18, v228
	v_mov_b32_e32 v19, v229
	v_mov_b32_e32 v20, v230
	v_mov_b32_e32 v21, v231
	v_pk_mul_f32 v[24:25], v[2:3], v[14:15] op_sel:[1,1] op_sel_hi:[0,1]
	v_pk_mul_f32 v[22:23], v[6:7], v[18:19] op_sel:[1,1] op_sel_hi:[0,1]
	v_mul_f32_e32 v0, v9, v21
	v_pk_mul_f32 v[10:11], v[6:7], v[18:19]
	v_pk_fma_f32 v[6:7], v[6:7], v[18:19], v[22:23] op_sel_hi:[1,0,1]
	v_pk_fma_f32 v[18:19], v[8:9], v[20:21], v[0:1] op_sel_hi:[1,1,0] neg_lo:[0,0,1] neg_hi:[0,0,1]
	v_mul_f32_e32 v0, v8, v21
	v_pk_fma_f32 v[20:21], v[8:9], v[20:21], v[0:1] op_sel:[1,0,0] op_sel_hi:[0,1,0]
	v_mul_f32_e32 v0, v5, v17
	v_pk_mul_f32 v[8:9], v[2:3], v[14:15]
	v_pk_fma_f32 v[2:3], v[2:3], v[14:15], v[24:25] op_sel_hi:[1,0,1]
	v_pk_fma_f32 v[14:15], v[4:5], v[16:17], v[0:1] op_sel_hi:[1,1,0] neg_lo:[0,0,1] neg_hi:[0,0,1]
	v_mul_f32_e32 v0, v4, v17
	v_pk_fma_f32 v[16:17], v[4:5], v[16:17], v[0:1] op_sel:[1,0,0] op_sel_hi:[0,1,0]
	v_sub_f32_e32 v6, v10, v22
	v_sub_f32_e32 v2, v8, v24
	v_mov_b32_e32 v8, v18
	v_mov_b32_e32 v9, v20
	v_mov_b32_e32 v4, v14
	v_mov_b32_e32 v5, v16
	s_branch .LBB0_427
